# GQA K LDS-DMA pieces use SGPR base + 32-bit VGPR offset; base advanced with SALU instead of two 64-bit VALU adds
# speedup vs baseline: 1.0026x; 1.0026x over previous
;   DI void init_offs() {
; #pragma unroll
;     for (int q = 0; q < NKL; ++q) {
;       const int c = tid + 256 * q, row = c / KCH, cc = c % KCH;
;       koff[q] = (DQK == 96 && cc >= 8) ? row * 32 + (cc - 8) * 8 : row * kpitch + cc * 8;
;     }
; #pragma unroll
;     for (int q = 0; q < 2; ++q) { const int c = tid + 256 * q, dv = c >> 3, kc = c & 7; voff[q] = dv * MPAD + kc * 8; }
;   }
;   DI void gload_k(int t) {
;     const int row0 = rowk0 + t * 64;
;     const u16* kt = Kb + (size_t)row0 * kpitch;
;     const u16* pt = KPEb + (size_t)row0 * 32;
; #pragma unroll
;     for (int q = 0; q < NKL; ++q) {
;       const int c = tid + 256 * q, cc = c % KCH;
;       rk[q] = ldg16(((DQK == 96 && cc >= 8) ? pt : kt) + koff[q]);
;     }
;   }
;   DI void gload_v(int t) {
;     const u16* vt = Vt + (rowk0 + t * 64);
; #pragma unroll
;     for (int q = 0; q < 2; ++q) rv[q] = ldg16(vt + voff[q]);
;   }
;   DI void sstore_k(int buf) {
; #pragma unroll
;     for (int q = 0; q < NKL; ++q) {
;       const int c = tid + 256 * q, row = c / KCH, cc = c % KCH;
;       *(u32x4*)(sK + buf * KBUF + row * KP + cc * 8) = rk[q];
;     }
;   }
; template <int DQK>
; DI void attn_item(const u16* __restrict__ Qb, int qpitch, const u16* __restrict__ Kb, int kpitch, const u16* __restrict__ KPEb,
;                   const u16* __restrict__ Vt, float* __restrict__ ssq, int rowq0, int rowk0, int nt, char* smem, int tid, bool dry) {
;     ...
;   c.gload_k(0); c.gload_v(0);
;   __syncthreads();
;   c.sstore_k(0); c.sstore_v(0);
;   if (nt > 1) c.gload_k(1);
;   __syncthreads();
;   c.qk(0, sa);
.Lg_entry:
	v_mov_b32_e32 v169, 0
	v_mov_b32_e32 v170, 0
	v_mov_b32_e32 v171, 0
	v_mov_b32_e32 v182, 0
	v_mov_b32_e32 v183, 0
	s_waitcnt vmcnt(0)
	v_lshrrev_b32_e32 v100, 3, v245
	v_and_b32_e32 v101, 7, v245
	v_bfe_u32 v102, v245, 4, 3
	v_xor_b32_e32 v101, v101, v102
	v_lshlrev_b32_e32 v101, 4, v101
	v_lshl_add_u32 v100, v100, 7, v101
	ds_write_b128 v100, v[152:155] offset:9216
	ds_write_b128 v100, v[156:159] offset:13312
	ds_write_b128 v100, v[160:163] offset:18432
	ds_write_b128 v100, v[164:167] offset:22528
	v_readfirstlane_b32 s47, v245
	s_nop 3
	s_lshr_b32 s47, s47, 6
	s_lshl_b32 s1, s47, 4
	v_lshrrev_b32_e32 v101, 3, v227
	v_lshrrev_b32_e32 v102, 4, v227
	v_and_b32_e32 v103, 7, v227
	v_xor_b32_e32 v103, v103, v102
	v_lshlrev_b32_e32 v103, 4, v103
	v_xor_b32_e32 v102, 64, v103
	v_add_u32_e32 v101, s1, v101
	v_lshl_add_u32 v104, v101, 8, v103
	v_lshl_add_u32 v106, v101, 8, v102
	v_add_u32_e32 v106, 0x400, v106
	v_mov_b32_e32 v105, 0
	v_mov_b32_e32 v107, 0
	v_mul_u32_u24_e32 v108, 0x20600, v101
	v_add_u32_e32 v110, v108, v102
	v_add_u32_e32 v108, v108, v103
	v_add_u32_e32 v110, 0x102c00, v110
	v_mov_b32_e32 v109, 0
	v_mov_b32_e32 v111, 0
	s_sub_i32 s0, s46, 64
	s_ashr_i32 s1, s0, 31
	s_lshl_b64 s[0:1], s[0:1], 8
	s_add_u32 s0, s26, s0
	s_addc_u32 s1, s27, s1
	v_mov_b32_e32 v214, v104
	v_mov_b32_e32 v216, v106
	s_mov_b64 s[20:21], s[0:1]
	s_add_i32 s0, s46, 0xffffff80
	s_ashr_i32 s1, s0, 31
	s_lshl_b64 s[0:1], s[0:1], 1
	s_add_u32 s0, s30, s0
	s_addc_u32 s1, s31, s1
	v_lshl_add_u64 v[160:161], v[108:109], 0, s[0:1]
	v_lshl_add_u64 v[162:163], v[110:111], 0, s[0:1]
	s_add_u32 s0, s0, 0x80
	s_addc_u32 s1, s1, 0
	v_lshl_add_u64 v[164:165], v[108:109], 0, s[0:1]
	v_lshl_add_u64 v[166:167], v[110:111], 0, s[0:1]
	s_lshl_b32 s46, s47, 11
	v_and_b32_e32 v100, 31, v227
	v_lshrrev_b32_e32 v101, 5, v227
	v_and_b32_e32 v102, 0x13, v100
	v_and_b32_e32 v103, 4, v100
	v_lshl_or_b32 v102, v103, 1, v102
	v_and_b32_e32 v103, 8, v100
	v_lshrrev_b32_e32 v103, 1, v103
	v_or_b32_e32 v102, v102, v103
	v_bfe_u32 v103, v102, 1, 3
	v_bfe_u32 v104, v100, 1, 3
	v_or_b32_e32 v105, 0, v101
	v_xor_b32_e32 v106, v105, v103
	v_lshlrev_b32_e32 v106, 4, v106
	v_lshl_add_u32 v152, v102, 7, v106
	v_xor_b32_e32 v106, v105, v104
	v_lshlrev_b32_e32 v106, 4, v106
	v_lshl_add_u32 v156, v100, 7, v106
	v_or_b32_e32 v105, 2, v101
	v_xor_b32_e32 v106, v105, v103
	v_lshlrev_b32_e32 v106, 4, v106
	v_lshl_add_u32 v153, v102, 7, v106
	v_xor_b32_e32 v106, v105, v104
	v_lshlrev_b32_e32 v106, 4, v106
	v_lshl_add_u32 v157, v100, 7, v106
	v_or_b32_e32 v105, 4, v101
	v_xor_b32_e32 v106, v105, v103
	v_lshlrev_b32_e32 v106, 4, v106
	v_lshl_add_u32 v154, v102, 7, v106
	v_xor_b32_e32 v106, v105, v104
	v_lshlrev_b32_e32 v106, 4, v106
	v_lshl_add_u32 v158, v100, 7, v106
	v_or_b32_e32 v105, 6, v101
	v_xor_b32_e32 v106, v105, v103
	v_lshlrev_b32_e32 v106, 4, v106
	v_lshl_add_u32 v155, v102, 7, v106
	v_xor_b32_e32 v106, v105, v104
	v_lshlrev_b32_e32 v106, 4, v106
	v_lshl_add_u32 v159, v100, 7, v106
	s_waitcnt lgkmcnt(0)
	s_barrier
	s_mov_b32 m0, s46
	s_nop 0
	global_load_lds_dwordx4 v214, s[20:21]
	global_load_lds_dwordx4 v216, s[20:21] offset:1024
	s_add_u32 s20, s20, 0x4000
	s_addc_u32 s21, s21, 0
	ds_read_b128 v[96:99], v152 offset:9216
	ds_read_b128 v[100:103], v152 offset:13312
	ds_read_b128 v[104:107], v153 offset:9216
	ds_read_b128 v[108:111], v153 offset:13312
	ds_read_b128 v[112:115], v154 offset:9216
	ds_read_b128 v[116:119], v154 offset:13312
	ds_read_b128 v[120:123], v155 offset:9216
	ds_read_b128 v[124:127], v155 offset:13312
	v_max3_f32 v128, v48, v32, v49
	v_max3_f32 v172, v33, v50, v34
	v_max3_f32 v128, v51, v35, v128
	v_max3_f32 v172, v52, v36, v172
	v_max3_f32 v128, v53, v37, v128
	v_max3_f32 v172, v54, v38, v172
	v_max3_f32 v128, v55, v39, v128
	v_max3_f32 v172, v56, v40, v172
	v_max3_f32 v128, v57, v41, v128
	v_max3_f32 v172, v58, v42, v172
	v_max3_f32 v128, v59, v43, v128
	v_max3_f32 v172, v60, v44, v172
	v_max3_f32 v128, v61, v45, v128
	v_max3_f32 v172, v62, v46, v172
	v_max3_f32 v128, v63, v47, v128
	v_max_f32_e32 v128, v128, v172
	v_and_b32_e32 v179, 0x7fff, v168
	v_cmp_ne_u32_e32 vcc, 0, v179
	s_cbranch_vccnz .LBB0_238

;   DI void gload_k(int t) {
;     const int row0 = rowk0 + t * 64;
;     const u16* kt = Kb + (size_t)row0 * kpitch;
;     const u16* pt = KPEb + (size_t)row0 * 32;
; #pragma unroll
;     for (int q = 0; q < NKL; ++q) {
;       const int c = tid + 256 * q, cc = c % KCH;
;       rk[q] = ldg16(((DQK == 96 && cc >= 8) ? pt : kt) + koff[q]);
;     }
;   }
;   template <int PAR>
;   DI void step(int t, f32x16 (&cur)[2], f32x16 (&nxt)[2]) {
;     ...
;     float psum = 0.f;
; #pragma unroll
;     for (int kb2 = 0; kb2 < 2; ++kb2)
; #pragma unroll
;       for (int i = 0; i < 16; ++i) { const float pv = __builtin_amdgcn_exp2f(cur[kb2][i]); cur[kb2][i] = pv; psum += pv; }
;     l += psum;
;     if (t + 2 < nt) gload_k(t + 2);
.Lgf_rareA_ret:
	v_exp_f32_e32 v48, v48
	v_exp_f32_e32 v49, v49
	v_exp_f32_e32 v50, v50
	v_add_f32_e32 v182, v48, v182
	v_exp_f32_e32 v51, v51
	v_add_f32_e32 v183, v49, v183
	v_exp_f32_e32 v52, v52
	v_add_f32_e32 v182, v50, v182
	s_waitcnt lgkmcnt(4)
	v_mfma_f32_32x32x16_bf16 v[80:95], v[96:99], v[136:139], 0
	v_exp_f32_e32 v53, v53
	v_add_f32_e32 v183, v51, v183
	v_exp_f32_e32 v54, v54
	v_add_f32_e32 v182, v52, v182
	v_exp_f32_e32 v55, v55
	v_add_f32_e32 v183, v53, v183
	v_mfma_f32_32x32x16_bf16 v[64:79], v[100:103], v[136:139], 0
	v_cvt_pk_bf16_f32 v48, v48, v49
	v_add_f32_e32 v182, v54, v182
	v_cvt_pk_bf16_f32 v49, v50, v51
	v_add_f32_e32 v183, v55, v183
	v_cvt_pk_bf16_f32 v50, v52, v53
	v_cvt_pk_bf16_f32 v51, v54, v55
	v_mfma_f32_32x32x16_bf16 v[80:95], v[104:107], v[140:143], v[80:95]
	v_exp_f32_e32 v56, v56
	v_exp_f32_e32 v57, v57
	v_exp_f32_e32 v58, v58
	v_add_f32_e32 v182, v56, v182
	v_exp_f32_e32 v59, v59
	v_add_f32_e32 v183, v57, v183
	v_mfma_f32_32x32x16_bf16 v[64:79], v[108:111], v[140:143], v[64:79]
	v_exp_f32_e32 v60, v60
	v_add_f32_e32 v182, v58, v182
	v_exp_f32_e32 v61, v61
	v_add_f32_e32 v183, v59, v183
	v_exp_f32_e32 v62, v62
	v_add_f32_e32 v182, v60, v182
	s_waitcnt vmcnt(0)
	s_waitcnt lgkmcnt(0)
	s_barrier
	s_add_i32 s0, s45, -1
	s_cmp_ge_u32 s0, s19
	s_cselect_b64 s[14:15], -1, 0
	s_cmp_ge_u32 s45, s19
	s_cbranch_scc1 .Lgf_skipKA
	s_add_i32 m0, s46, 9216
	s_nop 0
	global_load_lds_dwordx4 v214, s[20:21]
	global_load_lds_dwordx4 v216, s[20:21] offset:1024
	s_add_u32 s20, s20, 0x4000
	s_addc_u32 s21, s21, 0

;   DI void gload_k(int t) {
;     const int row0 = rowk0 + t * 64;
;     const u16* kt = Kb + (size_t)row0 * kpitch;
;     const u16* pt = KPEb + (size_t)row0 * 32;
; #pragma unroll
;     for (int q = 0; q < NKL; ++q) {
;       const int c = tid + 256 * q, cc = c % KCH;
;       rk[q] = ldg16(((DQK == 96 && cc >= 8) ? pt : kt) + koff[q]);
;     }
;   }
;   template <int PAR>
;   DI void step(int t, f32x16 (&cur)[2], f32x16 (&nxt)[2]) {
;     ...
;     float psum = 0.f;
; #pragma unroll
;     for (int kb2 = 0; kb2 < 2; ++kb2)
; #pragma unroll
;       for (int i = 0; i < 16; ++i) { const float pv = __builtin_amdgcn_exp2f(cur[kb2][i]); cur[kb2][i] = pv; psum += pv; }
;     l += psum;
;     if (t + 2 < nt) gload_k(t + 2);
.Lgf_rareB_ret:
	v_exp_f32_e32 v80, v80
	v_exp_f32_e32 v81, v81
	v_exp_f32_e32 v82, v82
	v_add_f32_e32 v182, v80, v182
	v_exp_f32_e32 v83, v83
	v_add_f32_e32 v183, v81, v183
	v_exp_f32_e32 v84, v84
	v_add_f32_e32 v182, v82, v182
	s_waitcnt lgkmcnt(4)
	v_mfma_f32_32x32x16_bf16 v[48:63], v[96:99], v[136:139], 0
	v_exp_f32_e32 v85, v85
	v_add_f32_e32 v183, v83, v183
	v_exp_f32_e32 v86, v86
	v_add_f32_e32 v182, v84, v182
	v_exp_f32_e32 v87, v87
	v_add_f32_e32 v183, v85, v183
	v_mfma_f32_32x32x16_bf16 v[32:47], v[100:103], v[136:139], 0
	v_cvt_pk_bf16_f32 v80, v80, v81
	v_add_f32_e32 v182, v86, v182
	v_cvt_pk_bf16_f32 v81, v82, v83
	v_add_f32_e32 v183, v87, v183
	v_cvt_pk_bf16_f32 v82, v84, v85
	v_cvt_pk_bf16_f32 v83, v86, v87
	v_mfma_f32_32x32x16_bf16 v[48:63], v[104:107], v[140:143], v[48:63]
	v_exp_f32_e32 v88, v88
	v_exp_f32_e32 v89, v89
	v_exp_f32_e32 v90, v90
	v_add_f32_e32 v182, v88, v182
	v_exp_f32_e32 v91, v91
	v_add_f32_e32 v183, v89, v183
	v_mfma_f32_32x32x16_bf16 v[32:47], v[108:111], v[140:143], v[32:47]
	v_exp_f32_e32 v92, v92
	v_add_f32_e32 v182, v90, v182
	v_exp_f32_e32 v93, v93
	v_add_f32_e32 v183, v91, v183
	v_exp_f32_e32 v94, v94
	v_add_f32_e32 v182, v92, v182
	s_waitcnt vmcnt(0)
	s_waitcnt lgkmcnt(0)
	s_barrier
	s_add_i32 s0, s45, 1
	s_cmp_ge_u32 s0, s19
	s_cbranch_scc1 .Lgf_skipKB
	s_add_i32 m0, s46, 0
	s_nop 0
	global_load_lds_dwordx4 v214, s[20:21]
	global_load_lds_dwordx4 v216, s[20:21] offset:1024
	s_add_u32 s20, s20, 0x4000
	s_addc_u32 s21, s21, 0

;   DI void gload_k(int t) {
;     const int row0 = rowk0 + t * 64;
;     const u16* kt = Kb + (size_t)row0 * kpitch;
;     const u16* pt = KPEb + (size_t)row0 * 32;
; #pragma unroll
;     for (int q = 0; q < NKL; ++q) {
;       const int c = tid + 256 * q, cc = c % KCH;
;       rk[q] = ldg16(((DQK == 96 && cc >= 8) ? pt : kt) + koff[q]);
;     }
;   }
;   template <int PAR>
;   DI void step(int t, f32x16 (&cur)[2], f32x16 (&nxt)[2]) {
;     ...
;     float psum = 0.f;
; #pragma unroll
;     for (int kb2 = 0; kb2 < 2; ++kb2)
; #pragma unroll
;       for (int i = 0; i < 16; ++i) { const float pv = __builtin_amdgcn_exp2f(cur[kb2][i]); cur[kb2][i] = pv; psum += pv; }
;     l += psum;
;     if (t + 2 < nt) gload_k(t + 2);
.Lg_rareA_ret:
	v_exp_f32_e32 v48, v48
	v_exp_f32_e32 v49, v49
	v_exp_f32_e32 v50, v50
	v_add_f32_e32 v182, v48, v182
	v_exp_f32_e32 v51, v51
	v_add_f32_e32 v183, v49, v183
	v_exp_f32_e32 v52, v52
	v_add_f32_e32 v182, v50, v182
	s_waitcnt lgkmcnt(4)
	v_mfma_f32_32x32x16_bf16 v[80:95], v[96:99], v[136:139], 0
	v_exp_f32_e32 v53, v53
	v_add_f32_e32 v183, v51, v183
	v_exp_f32_e32 v54, v54
	v_add_f32_e32 v182, v52, v182
	v_exp_f32_e32 v55, v55
	v_mfma_f32_32x32x16_bf16 v[64:79], v[100:103], v[136:139], 0
	v_add_f32_e32 v183, v53, v183
	v_cvt_pk_bf16_f32 v48, v48, v49
	v_add_f32_e32 v182, v54, v182
	v_cvt_pk_bf16_f32 v49, v50, v51
	v_add_f32_e32 v183, v55, v183
	v_mfma_f32_32x32x16_bf16 v[80:95], v[104:107], v[140:143], v[80:95]
	v_cvt_pk_bf16_f32 v50, v52, v53
	v_cvt_pk_bf16_f32 v51, v54, v55
	v_exp_f32_e32 v56, v56
	v_exp_f32_e32 v57, v57
	v_exp_f32_e32 v58, v58
	v_mfma_f32_32x32x16_bf16 v[64:79], v[108:111], v[140:143], v[64:79]
	v_add_f32_e32 v182, v56, v182
	v_exp_f32_e32 v59, v59
	v_add_f32_e32 v183, v57, v183
	v_exp_f32_e32 v60, v60
	v_add_f32_e32 v182, v58, v182
	s_waitcnt vmcnt(0)
	s_waitcnt lgkmcnt(0)
	s_barrier
	s_add_i32 s0, s45, -1
	s_cmp_ge_u32 s0, s19
	s_cselect_b64 s[14:15], -1, 0
	s_cmp_ge_u32 s45, s19
	s_cbranch_scc1 .Lg_skipKA
	s_add_i32 m0, s46, 9216
	s_nop 0
	global_load_lds_dwordx4 v214, s[20:21]
	global_load_lds_dwordx4 v216, s[20:21] offset:1024
	s_add_u32 s20, s20, 0x4000
	s_addc_u32 s21, s21, 0

;   DI void gload_k(int t) {
;     const int row0 = rowk0 + t * 64;
;     const u16* kt = Kb + (size_t)row0 * kpitch;
;     const u16* pt = KPEb + (size_t)row0 * 32;
; #pragma unroll
;     for (int q = 0; q < NKL; ++q) {
;       const int c = tid + 256 * q, cc = c % KCH;
;       rk[q] = ldg16(((DQK == 96 && cc >= 8) ? pt : kt) + koff[q]);
;     }
;   }
;   template <int PAR>
;   DI void step(int t, f32x16 (&cur)[2], f32x16 (&nxt)[2]) {
;     ...
;     float psum = 0.f;
; #pragma unroll
;     for (int kb2 = 0; kb2 < 2; ++kb2)
; #pragma unroll
;       for (int i = 0; i < 16; ++i) { const float pv = __builtin_amdgcn_exp2f(cur[kb2][i]); cur[kb2][i] = pv; psum += pv; }
;     l += psum;
;     if (t + 2 < nt) gload_k(t + 2);
.Lg_rareB_ret:
	v_exp_f32_e32 v80, v80
	v_exp_f32_e32 v81, v81
	v_exp_f32_e32 v82, v82
	v_add_f32_e32 v182, v80, v182
	v_exp_f32_e32 v83, v83
	v_add_f32_e32 v183, v81, v183
	v_exp_f32_e32 v84, v84
	v_add_f32_e32 v182, v82, v182
	s_waitcnt lgkmcnt(4)
	v_mfma_f32_32x32x16_bf16 v[48:63], v[96:99], v[136:139], 0
	v_exp_f32_e32 v85, v85
	v_add_f32_e32 v183, v83, v183
	v_exp_f32_e32 v86, v86
	v_add_f32_e32 v182, v84, v182
	v_exp_f32_e32 v87, v87
	v_mfma_f32_32x32x16_bf16 v[32:47], v[100:103], v[136:139], 0
	v_add_f32_e32 v183, v85, v183
	v_cvt_pk_bf16_f32 v80, v80, v81
	v_add_f32_e32 v182, v86, v182
	v_cvt_pk_bf16_f32 v81, v82, v83
	v_add_f32_e32 v183, v87, v183
	v_mfma_f32_32x32x16_bf16 v[48:63], v[104:107], v[140:143], v[48:63]
	v_cvt_pk_bf16_f32 v82, v84, v85
	v_cvt_pk_bf16_f32 v83, v86, v87
	v_exp_f32_e32 v88, v88
	v_exp_f32_e32 v89, v89
	v_exp_f32_e32 v90, v90
	v_mfma_f32_32x32x16_bf16 v[32:47], v[108:111], v[140:143], v[32:47]
	v_add_f32_e32 v182, v88, v182
	v_exp_f32_e32 v91, v91
	v_add_f32_e32 v183, v89, v183
	v_exp_f32_e32 v92, v92
	v_add_f32_e32 v182, v90, v182
	s_waitcnt vmcnt(0)
	s_waitcnt lgkmcnt(0)
	s_barrier
	s_add_i32 s0, s45, 1
	s_cmp_ge_u32 s0, s19
	s_cbranch_scc1 .Lg_skipKB
	s_add_i32 m0, s46, 0
	s_nop 0
	global_load_lds_dwordx4 v214, s[20:21]
	global_load_lds_dwordx4 v216, s[20:21] offset:1024
	s_add_u32 s20, s20, 0x4000
	s_addc_u32 s21, s21, 0
